# all six 512-tile GEMM phases (down, out) walk tiles in reverse order: consume most recently written rows first
# speedup vs baseline: 1.0018x; 1.0018x over previous
;     __host__ __device__ bool next(int i, Unit& u) const {
;         const long L = (long)i * G + c; if (L >= nwg) return false;
;         int wgid = (int)L; { const int q = nwg / NXCD, r = nwg % NXCD, xcd = wgid % NXCD, off = wgid / NXCD; wgid = (xcd < r ? xcd * (q + 1) : r * (q + 1) + (xcd - r) * q) + off; }
;         const int nig = WGM * nN, gid = wgid / nig, fm = gid * WGM, gsz = (nM - fm) < WGM ? (nM - fm) : WGM;
;         u.pm = fm + ((wgid % nig) % gsz); u.pn = (wgid % nig) / gsz; return true;
; template <class Epi, class Sched, bool ALIGN_EPI = false, bool SP2 = false>
; __device__ __forceinline__ void gemm_phase(PG8_LAS unsigned char* lds, const Gemm g, const Sched& S, const Epi& E) {
;     ...
;     if (!S.next(0, cur)) return;
.LBB0_1198:
	s_cmpk_lt_i32 s18, 0x200
	s_movk_i32 s0, 0x400
	s_cselect_b64 s[2:3], -1, 0
	s_cmpk_gt_i32 s18, 0x1ff
	v_readfirstlane_b32 s26, v254
	s_cbranch_scc1 .LBB0_1204
	s_sub_i32 s99, 0x1ff, s18
	s_ashr_i32 s1, s99, 31
	s_lshr_b32 s1, s1, 29
	s_add_i32 s1, s99, s1
	s_and_b32 s4, s1, -8
	s_sub_i32 s6, s99, s4
	s_cmp_gt_i32 s6, -1
	s_cbranch_scc0 .LBB0_1201
	s_lshl_b32 s7, s6, 6
	s_cbranch_execz .LBB0_1202
	s_branch .LBB0_1203

;     __host__ __device__ bool next(int i, Unit& u) const {
;         const long L = (long)i * G + c; if (L >= nwg) return false;
;         int wgid = (int)L; { const int q = nwg / NXCD, r = nwg % NXCD, xcd = wgid % NXCD, off = wgid / NXCD; wgid = (xcd < r ? xcd * (q + 1) : r * (q + 1) + (xcd - r) * q) + off; }
;         const int nig = WGM * nN, gid = wgid / nig, fm = gid * WGM, gsz = (nM - fm) < WGM ? (nM - fm) : WGM;
;         u.pm = fm + ((wgid % nig) % gsz); u.pn = (wgid % nig) / gsz; return true;
; template <class Epi, class Sched, bool ALIGN_EPI = false, bool SP2 = false>
; __device__ __forceinline__ void gemm_phase(PG8_LAS unsigned char* lds, const Gemm g, const Sched& S, const Epi& E) {
;     ...
;         const bool has_next = S.next(ui + 1, nxt);
;         const char* nA = has_next ? (const char*)g.A + (size_t)nxt.pm * tstep : cA; const char* nB = has_next ? (const char*)g.Bt + (size_t)nxt.pn * tstep : cB;
.LBB0_1210:
	v_lshl_add_u32 v252, s62, 8, v148
	v_lshl_or_b32 v253, s14, 8, v150
	v_lshlrev_b32_e32 v253, 1, v253
	v_lshl_add_u32 v252, v252, 11, v253
	global_load_dwordx4 v[230:233], v252, s[42:43]
	global_load_dwordx4 v[234:237], v252, s[42:43] offset:256
	v_add_u32_e32 v253, 0x8000, v252
	global_load_dwordx4 v[238:241], v253, s[42:43]
	global_load_dwordx4 v[242:245], v253, s[42:43] offset:256
	v_add_u32_e32 v253, 0x10000, v252
	global_load_dwordx4 v[246:249], v253, s[42:43]
	global_load_dwordx4 v[250:253], v253, s[42:43] offset:256
	s_add_i32 s59, s59, 1
	s_mul_i32 s0, s59, s50
	s_mul_hi_u32 s1, s59, s51
	s_add_i32 s1, s1, s0
	s_mul_i32 s0, s59, s51
	s_add_u32 s4, s0, s18
	s_addc_u32 s5, s1, s56
	v_cmp_gt_i64_e32 vcc, s[4:5], v[142:143]
	v_cmp_lt_i64_e64 s[0:1], s[4:5], v[140:141]
	s_cbranch_vccnz .LBB0_1216
	s_sub_i32 s4, 0x1ff, s4
	s_ashr_i32 s5, s4, 31
	s_lshr_b32 s5, s5, 29
	s_add_i32 s28, s4, s5
	s_and_b32 s5, s28, -8
	s_sub_i32 s29, s4, s5
	s_cmp_gt_i32 s29, -1
	s_mov_b64 s[4:5], -1
	s_cbranch_scc0 .LBB0_1213
	s_lshl_b32 s60, s29, 6
	s_mov_b64 s[4:5], 0

;     __host__ __device__ bool next(int i, Unit& u) const {
;         const long L = (long)i * G + c; if (L >= nwg) return false;
;         int wgid = (int)L; { const int q = nwg / NXCD, r = nwg % NXCD, xcd = wgid % NXCD, off = wgid / NXCD; wgid = (xcd < r ? xcd * (q + 1) : r * (q + 1) + (xcd - r) * q) + off; }
;         const int nig = WGM * nN, gid = wgid / nig, fm = gid * WGM, gsz = (nM - fm) < WGM ? (nM - fm) : WGM;
;         u.pm = fm + ((wgid % nig) % gsz); u.pn = (wgid % nig) / gsz; return true;
; template <class Epi, class Sched, bool ALIGN_EPI = false, bool SP2 = false>
; __device__ __forceinline__ void gemm_phase(PG8_LAS unsigned char* lds, const Gemm g, const Sched& S, const Epi& E) {
;     ...
;         const bool has_next = S.next(ui + 1, nxt);
;         const char* nA = has_next ? (const char*)g.A + (size_t)nxt.pm * tstep : cA; const char* nB = has_next ? (const char*)g.Bt + (size_t)nxt.pn * tstep : cB;
.LBB0_2374:
	v_lshl_add_u32 v252, s60, 8, v148
	v_lshl_or_b32 v253, s14, 8, v150
	v_lshlrev_b32_e32 v253, 1, v253
	v_lshl_add_u32 v252, v252, 11, v253
	global_load_dwordx4 v[230:233], v252, s[42:43]
	global_load_dwordx4 v[234:237], v252, s[42:43] offset:256
	v_add_u32_e32 v253, 0x8000, v252
	global_load_dwordx4 v[238:241], v253, s[42:43]
	global_load_dwordx4 v[242:245], v253, s[42:43] offset:256
	v_add_u32_e32 v253, 0x10000, v252
	global_load_dwordx4 v[246:249], v253, s[42:43]
	global_load_dwordx4 v[250:253], v253, s[42:43] offset:256
	s_add_i32 s57, s57, 1
	s_mul_i32 s0, s57, s44
	s_mul_hi_u32 s1, s57, s45
	s_add_i32 s1, s1, s0
	s_mul_i32 s0, s57, s45
	s_add_u32 s4, s0, s18
	s_addc_u32 s5, s1, s50
	v_cmp_gt_i64_e32 vcc, s[4:5], v[142:143]
	v_cmp_lt_i64_e64 s[0:1], s[4:5], v[140:141]
	s_cbranch_vccnz .LBB0_2380
	s_sub_i32 s4, 0x1ff, s4
	s_ashr_i32 s5, s4, 31
	s_lshr_b32 s5, s5, 29
	s_add_i32 s28, s4, s5
	s_and_b32 s5, s28, -8
	s_sub_i32 s29, s4, s5
	s_cmp_gt_i32 s29, -1
	s_mov_b64 s[4:5], -1
	s_cbranch_scc0 .LBB0_2377
	s_lshl_b32 s58, s29, 6
	s_mov_b64 s[4:5], 0
